# DA latent pipelined ring loop: ring deepened to 8 slots in LDS [0,128K) (DMA lead 7 tiles), tail junk DMAs redirected to dummy LDS
# baseline (speedup 1.0000x reference)
.Lmy_pp_srcdone:
	s_nop 0
	v_lshl_add_u64 v[242:243], s[28:29], 0, v[242:243]
	v_mov_b32_e32 v245, 0
	v_mov_b32_e32 v246, v150
	s_lshr_b32 s28, s25, 2
	s_lshl_b32 s28, s28, 12
	s_lshl_b32 s26, s25, 11
	v_add_u32_e32 v247, s28, v246
	s_mov_b32 m0, s26
	s_nop 0
	global_load_lds_dwordx4 v[242:243], off
	global_load_lds_dwordx4 v[242:243], off offset:1024
	v_lshl_add_u64 v[242:243], v[244:245], 0, v[242:243]
	s_add_i32 m0, s26, 0x4000
	s_nop 0
	global_load_lds_dwordx4 v[242:243], off
	global_load_lds_dwordx4 v[242:243], off offset:1024
	v_lshl_add_u64 v[242:243], v[244:245], 0, v[242:243]
	s_add_i32 m0, s26, 0x8000
	s_nop 0
	global_load_lds_dwordx4 v[242:243], off
	global_load_lds_dwordx4 v[242:243], off offset:1024
	v_lshl_add_u64 v[242:243], v[244:245], 0, v[242:243]
	s_add_i32 m0, s26, 0xc000
	s_nop 0
	global_load_lds_dwordx4 v[242:243], off
	global_load_lds_dwordx4 v[242:243], off offset:1024
	v_lshl_add_u64 v[242:243], v[244:245], 0, v[242:243]
	s_add_i32 m0, s26, 0x10000
	s_nop 0
	global_load_lds_dwordx4 v[242:243], off
	global_load_lds_dwordx4 v[242:243], off offset:1024
	v_lshl_add_u64 v[242:243], v[244:245], 0, v[242:243]
	s_add_i32 m0, s26, 0x14000
	s_nop 0
	global_load_lds_dwordx4 v[242:243], off
	global_load_lds_dwordx4 v[242:243], off offset:1024
	v_lshl_add_u64 v[242:243], v[244:245], 0, v[242:243]
	s_add_i32 m0, s26, 0x18000
	s_nop 0
	global_load_lds_dwordx4 v[242:243], off
	global_load_lds_dwordx4 v[242:243], off offset:1024
	v_lshl_add_u64 v[242:243], v[244:245], 0, v[242:243]
	s_mov_b32 s24, 0x1c000
	s_lshr_b32 s29, s25, 2
	s_mov_b32 s25, 0
	s_waitcnt vmcnt(12)
	s_barrier
.Lmy_pp_loop2:
	v_add_u32_e32 v248, s25, v246
	v_add_u32_e32 v249, s25, v247
	ds_read_b128 v[144:147], v248 offset:8192
	ds_read_b128 v[136:139], v248 offset:10240
	ds_read_b128 v[132:135], v248 offset:12288
	ds_read_b128 v[116:119], v248 offset:14336
	ds_read_b128 v[128:131], v248 offset:9216
	ds_read_b128 v[140:143], v248 offset:11264
	ds_read_b128 v[124:127], v248 offset:13312
	ds_read_b128 v[120:123], v248 offset:15360
	v_mfma_f32_32x32x16_bf16 v[218:233], v[112:115], v[108:111], 0
	v_max3_f32 v14, v80, v81, v82
	v_max3_f32 v15, v83, v84, v85
	v_max3_f32 v209, v86, v87, v88
	s_add_i32 s27, s24, s26
	s_sub_i32 s28, 8, s29
	s_cmp_gt_u32 s13, s28
	s_cselect_b32 m0, s27, 0x20000
	s_add_i32 s28, s28, 1
	s_cmp_gt_u32 s13, s28
	s_cselect_b32 s28, -1, 0
	v_mfma_f32_32x32x16_bf16 v[218:233], v[10:13], v[104:107], v[218:233]
	v_max3_f32 v212, v89, v90, v91
	v_max3_f32 v14, v14, v92, v93
	v_max3_f32 v15, v15, v94, v95
	global_load_lds_dwordx4 v[242:243], off
	global_load_lds_dwordx4 v[242:243], off offset:1024
	v_mfma_f32_32x32x16_bf16 v[218:233], v[6:9], v[100:103], v[218:233]
	v_and_b32_e32 v244, s28, v244
	v_max3_f32 v14, v14, v15, v209
	v_max_f32_e32 v14, v14, v212
	v_lshl_add_u64 v[242:243], v[244:245], 0, v[242:243]
	v_mov_b32_e32 v15, v14
	s_add_i32 s24, s24, 0x4000
	s_and_b32 s24, s24, 0x1c000
	v_mfma_f32_32x32x16_bf16 v[218:233], v[2:5], v[96:99], v[218:233]
	v_permlane32_swap_b32_e32 v14, v15
	ds_read_b128 v[112:115], v249
	ds_read_b128 v[10:13], v249 offset:1024
	ds_read_b128 v[6:9], v249 offset:2048
	ds_read_b128 v[2:5], v249 offset:3072
	s_add_i32 s25, s25, 0x4000
	s_and_b32 s25, s25, 0x1c000
	v_max_f32_e32 v14, v14, v15
	v_add_f32_e32 v15, 0x41000000, v208
	v_cmp_gt_f32_e32 vcc, v14, v15
	s_cbranch_vccz .Lmy_pp_nors_a
	v_max_f32_e32 v15, v208, v14
	v_sub_f32_e32 v14, v208, v15
	v_exp_f32_e32 v14, v14
	v_mov_b32_e32 v208, v15
	s_nop 0
	v_mul_f32_e32 v0, v0, v14
	v_pk_mul_f32 v[78:79], v[78:79], v[14:15] op_sel_hi:[1,0]
	v_pk_mul_f32 v[76:77], v[76:77], v[14:15] op_sel_hi:[1,0]
	v_pk_mul_f32 v[74:75], v[74:75], v[14:15] op_sel_hi:[1,0]
	v_pk_mul_f32 v[72:73], v[72:73], v[14:15] op_sel_hi:[1,0]
	v_pk_mul_f32 v[70:71], v[70:71], v[14:15] op_sel_hi:[1,0]
	v_pk_mul_f32 v[68:69], v[68:69], v[14:15] op_sel_hi:[1,0]
	v_pk_mul_f32 v[66:67], v[66:67], v[14:15] op_sel_hi:[1,0]
	v_pk_mul_f32 v[64:65], v[64:65], v[14:15] op_sel_hi:[1,0]
	v_pk_mul_f32 v[62:63], v[62:63], v[14:15] op_sel_hi:[1,0]
	v_pk_mul_f32 v[60:61], v[60:61], v[14:15] op_sel_hi:[1,0]
	v_pk_mul_f32 v[58:59], v[58:59], v[14:15] op_sel_hi:[1,0]
	v_pk_mul_f32 v[56:57], v[56:57], v[14:15] op_sel_hi:[1,0]
	v_pk_mul_f32 v[54:55], v[54:55], v[14:15] op_sel_hi:[1,0]
	v_pk_mul_f32 v[52:53], v[52:53], v[14:15] op_sel_hi:[1,0]
	v_pk_mul_f32 v[50:51], v[50:51], v[14:15] op_sel_hi:[1,0]
	v_pk_mul_f32 v[48:49], v[48:49], v[14:15] op_sel_hi:[1,0]
	v_pk_mul_f32 v[46:47], v[46:47], v[14:15] op_sel_hi:[1,0]
	v_pk_mul_f32 v[44:45], v[44:45], v[14:15] op_sel_hi:[1,0]
	v_pk_mul_f32 v[42:43], v[42:43], v[14:15] op_sel_hi:[1,0]
	v_pk_mul_f32 v[40:41], v[40:41], v[14:15] op_sel_hi:[1,0]
	v_pk_mul_f32 v[38:39], v[38:39], v[14:15] op_sel_hi:[1,0]
	v_pk_mul_f32 v[36:37], v[36:37], v[14:15] op_sel_hi:[1,0]
	v_pk_mul_f32 v[34:35], v[34:35], v[14:15] op_sel_hi:[1,0]
	v_pk_mul_f32 v[32:33], v[32:33], v[14:15] op_sel_hi:[1,0]
	v_pk_mul_f32 v[30:31], v[30:31], v[14:15] op_sel_hi:[1,0]
	v_pk_mul_f32 v[28:29], v[28:29], v[14:15] op_sel_hi:[1,0]
	v_pk_mul_f32 v[26:27], v[26:27], v[14:15] op_sel_hi:[1,0]
	v_pk_mul_f32 v[24:25], v[24:25], v[14:15] op_sel_hi:[1,0]
	v_pk_mul_f32 v[22:23], v[22:23], v[14:15] op_sel_hi:[1,0]
	v_pk_mul_f32 v[20:21], v[20:21], v[14:15] op_sel_hi:[1,0]
	v_pk_mul_f32 v[18:19], v[18:19], v[14:15] op_sel_hi:[1,0]
	v_pk_mul_f32 v[16:17], v[16:17], v[14:15] op_sel_hi:[1,0]
.Lmy_pp_nors_a:
	s_cmp_eq_u32 s29, 0
	s_cbranch_scc1 .Lmy_pp_nbm_a
	s_waitcnt vmcnt(12) lgkmcnt(0)
	s_barrier
.Lmy_pp_nbm_a:
	v_sub_f32_e32 v14, v80, v208
	v_exp_f32_e32 v14, v14
	v_sub_f32_e32 v80, v81, v208
	v_exp_f32_e32 v80, v80
	v_sub_f32_e32 v81, v82, v208
	v_exp_f32_e32 v81, v81
	v_sub_f32_e32 v82, v83, v208
	v_exp_f32_e32 v82, v82
	v_sub_f32_e32 v83, v84, v208
	v_sub_f32_e32 v84, v85, v208
	v_sub_f32_e32 v85, v86, v208
	v_sub_f32_e32 v86, v87, v208
	v_add_f32_e32 v15, 0, v14
	v_exp_f32_e32 v83, v83
	v_exp_f32_e32 v84, v84
	v_exp_f32_e32 v85, v85
	v_exp_f32_e32 v86, v86
	v_add_f32_e32 v15, v80, v15
	v_add_f32_e32 v15, v81, v15
	v_add_f32_e32 v15, v82, v15
	v_add_f32_e32 v15, v83, v15
	v_cvt_pk_bf16_f32 v80, v14, v80
	v_cvt_pk_bf16_f32 v81, v81, v82
	v_cvt_pk_bf16_f32 v82, v83, v84
	v_cvt_pk_bf16_f32 v83, v85, v86
	v_sub_f32_e32 v87, v88, v208
	v_sub_f32_e32 v88, v89, v208
	s_waitcnt lgkmcnt(4)
	v_mfma_f32_32x32x16_bf16 v[64:79], v[144:147], v[80:83], v[64:79]
	v_sub_f32_e32 v89, v90, v208
	v_sub_f32_e32 v90, v91, v208
	v_sub_f32_e32 v91, v92, v208
	v_exp_f32_e32 v87, v87
	v_exp_f32_e32 v88, v88
	v_mfma_f32_32x32x16_bf16 v[48:63], v[136:139], v[80:83], v[48:63]
	v_sub_f32_e32 v92, v93, v208
	v_sub_f32_e32 v93, v94, v208
	v_sub_f32_e32 v94, v95, v208
	v_exp_f32_e32 v89, v89
	v_exp_f32_e32 v90, v90
	v_mfma_f32_32x32x16_bf16 v[32:47], v[132:135], v[80:83], v[32:47]
	v_exp_f32_e32 v91, v91
	v_exp_f32_e32 v92, v92
	v_exp_f32_e32 v93, v93
	v_exp_f32_e32 v94, v94
	v_mfma_f32_32x32x16_bf16 v[16:31], v[116:119], v[80:83], v[16:31]
	v_add_f32_e32 v15, v84, v15
	v_add_f32_e32 v15, v85, v15
	v_add_f32_e32 v15, v86, v15
	v_add_f32_e32 v15, v87, v15
	v_cvt_pk_bf16_f32 v84, v87, v88
	v_cvt_pk_bf16_f32 v85, v89, v90
	v_cvt_pk_bf16_f32 v86, v91, v92
	v_cvt_pk_bf16_f32 v87, v93, v94
	v_add_f32_e32 v15, v88, v15
	v_add_f32_e32 v15, v89, v15
	v_mfma_f32_32x32x16_bf16 v[64:79], v[128:131], v[84:87], v[64:79]
	v_add_f32_e32 v15, v90, v15
	v_add_f32_e32 v15, v91, v15
	s_add_i32 s13, s13, -1
	v_mfma_f32_32x32x16_bf16 v[48:63], v[140:143], v[84:87], v[48:63]
	v_add_f32_e32 v15, v92, v15
	v_add_f32_e32 v15, v93, v15
	v_mfma_f32_32x32x16_bf16 v[32:47], v[124:127], v[84:87], v[32:47]
	v_add_f32_e32 v15, v94, v15
	v_add_f32_e32 v0, v0, v15
	v_mfma_f32_32x32x16_bf16 v[16:31], v[120:123], v[84:87], v[16:31]
	s_cmp_lg_u32 s29, 0
	s_cbranch_scc1 .Lmy_pp_nbe_a
	s_waitcnt vmcnt(12) lgkmcnt(0)
	s_barrier
.Lmy_pp_nbe_a:
	v_add_u32_e32 v248, s25, v246
	v_add_u32_e32 v249, s25, v247
	ds_read_b128 v[144:147], v248 offset:8192
	ds_read_b128 v[136:139], v248 offset:10240
	ds_read_b128 v[132:135], v248 offset:12288
	ds_read_b128 v[116:119], v248 offset:14336
	ds_read_b128 v[128:131], v248 offset:9216
	ds_read_b128 v[140:143], v248 offset:11264
	ds_read_b128 v[124:127], v248 offset:13312
	ds_read_b128 v[120:123], v248 offset:15360
	v_mfma_f32_32x32x16_bf16 v[80:95], v[112:115], v[108:111], 0
	v_max3_f32 v14, v218, v219, v220
	v_max3_f32 v15, v221, v222, v223
	v_max3_f32 v209, v224, v225, v226
	s_add_i32 s27, s24, s26
	s_sub_i32 s28, 8, s29
	s_cmp_gt_u32 s13, s28
	s_cselect_b32 m0, s27, 0x20000
	s_add_i32 s28, s28, 1
	s_cmp_gt_u32 s13, s28
	s_cselect_b32 s28, -1, 0
	v_mfma_f32_32x32x16_bf16 v[80:95], v[10:13], v[104:107], v[80:95]
	v_max3_f32 v212, v227, v228, v229
	v_max3_f32 v14, v14, v230, v231
	v_max3_f32 v15, v15, v232, v233
	global_load_lds_dwordx4 v[242:243], off
	global_load_lds_dwordx4 v[242:243], off offset:1024
	v_mfma_f32_32x32x16_bf16 v[80:95], v[6:9], v[100:103], v[80:95]
	v_and_b32_e32 v244, s28, v244
	v_max3_f32 v14, v14, v15, v209
	v_max_f32_e32 v14, v14, v212
	v_lshl_add_u64 v[242:243], v[244:245], 0, v[242:243]
	v_mov_b32_e32 v15, v14
	s_add_i32 s24, s24, 0x4000
	s_and_b32 s24, s24, 0x1c000
	v_mfma_f32_32x32x16_bf16 v[80:95], v[2:5], v[96:99], v[80:95]
	v_permlane32_swap_b32_e32 v14, v15
	ds_read_b128 v[112:115], v249
	ds_read_b128 v[10:13], v249 offset:1024
	ds_read_b128 v[6:9], v249 offset:2048
	ds_read_b128 v[2:5], v249 offset:3072
	s_add_i32 s25, s25, 0x4000
	s_and_b32 s25, s25, 0x1c000
	v_max_f32_e32 v14, v14, v15
	v_add_f32_e32 v15, 0x41000000, v208
	v_cmp_gt_f32_e32 vcc, v14, v15
	s_cbranch_vccz .Lmy_pp_nors_b
	v_max_f32_e32 v15, v208, v14
	v_sub_f32_e32 v14, v208, v15
	v_exp_f32_e32 v14, v14
	v_mov_b32_e32 v208, v15
	s_nop 0
	v_mul_f32_e32 v0, v0, v14
	v_pk_mul_f32 v[78:79], v[78:79], v[14:15] op_sel_hi:[1,0]
	v_pk_mul_f32 v[76:77], v[76:77], v[14:15] op_sel_hi:[1,0]
	v_pk_mul_f32 v[74:75], v[74:75], v[14:15] op_sel_hi:[1,0]
	v_pk_mul_f32 v[72:73], v[72:73], v[14:15] op_sel_hi:[1,0]
	v_pk_mul_f32 v[70:71], v[70:71], v[14:15] op_sel_hi:[1,0]
	v_pk_mul_f32 v[68:69], v[68:69], v[14:15] op_sel_hi:[1,0]
	v_pk_mul_f32 v[66:67], v[66:67], v[14:15] op_sel_hi:[1,0]
	v_pk_mul_f32 v[64:65], v[64:65], v[14:15] op_sel_hi:[1,0]
	v_pk_mul_f32 v[62:63], v[62:63], v[14:15] op_sel_hi:[1,0]
	v_pk_mul_f32 v[60:61], v[60:61], v[14:15] op_sel_hi:[1,0]
	v_pk_mul_f32 v[58:59], v[58:59], v[14:15] op_sel_hi:[1,0]
	v_pk_mul_f32 v[56:57], v[56:57], v[14:15] op_sel_hi:[1,0]
	v_pk_mul_f32 v[54:55], v[54:55], v[14:15] op_sel_hi:[1,0]
	v_pk_mul_f32 v[52:53], v[52:53], v[14:15] op_sel_hi:[1,0]
	v_pk_mul_f32 v[50:51], v[50:51], v[14:15] op_sel_hi:[1,0]
	v_pk_mul_f32 v[48:49], v[48:49], v[14:15] op_sel_hi:[1,0]
	v_pk_mul_f32 v[46:47], v[46:47], v[14:15] op_sel_hi:[1,0]
	v_pk_mul_f32 v[44:45], v[44:45], v[14:15] op_sel_hi:[1,0]
	v_pk_mul_f32 v[42:43], v[42:43], v[14:15] op_sel_hi:[1,0]
	v_pk_mul_f32 v[40:41], v[40:41], v[14:15] op_sel_hi:[1,0]
	v_pk_mul_f32 v[38:39], v[38:39], v[14:15] op_sel_hi:[1,0]
	v_pk_mul_f32 v[36:37], v[36:37], v[14:15] op_sel_hi:[1,0]
	v_pk_mul_f32 v[34:35], v[34:35], v[14:15] op_sel_hi:[1,0]
	v_pk_mul_f32 v[32:33], v[32:33], v[14:15] op_sel_hi:[1,0]
	v_pk_mul_f32 v[30:31], v[30:31], v[14:15] op_sel_hi:[1,0]
	v_pk_mul_f32 v[28:29], v[28:29], v[14:15] op_sel_hi:[1,0]
	v_pk_mul_f32 v[26:27], v[26:27], v[14:15] op_sel_hi:[1,0]
	v_pk_mul_f32 v[24:25], v[24:25], v[14:15] op_sel_hi:[1,0]
	v_pk_mul_f32 v[22:23], v[22:23], v[14:15] op_sel_hi:[1,0]
	v_pk_mul_f32 v[20:21], v[20:21], v[14:15] op_sel_hi:[1,0]
	v_pk_mul_f32 v[18:19], v[18:19], v[14:15] op_sel_hi:[1,0]
	v_pk_mul_f32 v[16:17], v[16:17], v[14:15] op_sel_hi:[1,0]

.Lmy_pp_nbm_b:
	v_sub_f32_e32 v14, v218, v208
	v_exp_f32_e32 v14, v14
	v_sub_f32_e32 v218, v219, v208
	v_exp_f32_e32 v218, v218
	v_sub_f32_e32 v219, v220, v208
	v_exp_f32_e32 v219, v219
	v_sub_f32_e32 v220, v221, v208
	v_exp_f32_e32 v220, v220
	v_sub_f32_e32 v221, v222, v208
	v_sub_f32_e32 v222, v223, v208
	v_sub_f32_e32 v223, v224, v208
	v_sub_f32_e32 v224, v225, v208
	v_add_f32_e32 v15, 0, v14
	v_exp_f32_e32 v221, v221
	v_exp_f32_e32 v222, v222
	v_exp_f32_e32 v223, v223
	v_exp_f32_e32 v224, v224
	v_add_f32_e32 v15, v218, v15
	v_add_f32_e32 v15, v219, v15
	v_add_f32_e32 v15, v220, v15
	v_add_f32_e32 v15, v221, v15
	v_cvt_pk_bf16_f32 v218, v14, v218
	v_cvt_pk_bf16_f32 v219, v219, v220
	v_cvt_pk_bf16_f32 v220, v221, v222
	v_cvt_pk_bf16_f32 v221, v223, v224
	v_sub_f32_e32 v225, v226, v208
	v_sub_f32_e32 v226, v227, v208
	s_waitcnt lgkmcnt(4)
	v_mfma_f32_32x32x16_bf16 v[64:79], v[144:147], v[218:221], v[64:79]
	v_sub_f32_e32 v227, v228, v208
	v_sub_f32_e32 v228, v229, v208
	v_sub_f32_e32 v229, v230, v208
	v_exp_f32_e32 v225, v225
	v_exp_f32_e32 v226, v226
	v_mfma_f32_32x32x16_bf16 v[48:63], v[136:139], v[218:221], v[48:63]
	v_sub_f32_e32 v230, v231, v208
	v_sub_f32_e32 v231, v232, v208
	v_sub_f32_e32 v232, v233, v208
	v_exp_f32_e32 v227, v227
	v_exp_f32_e32 v228, v228
	v_mfma_f32_32x32x16_bf16 v[32:47], v[132:135], v[218:221], v[32:47]
	v_exp_f32_e32 v229, v229
	v_exp_f32_e32 v230, v230
	v_exp_f32_e32 v231, v231
	v_exp_f32_e32 v232, v232
	v_mfma_f32_32x32x16_bf16 v[16:31], v[116:119], v[218:221], v[16:31]
	v_add_f32_e32 v15, v222, v15
	v_add_f32_e32 v15, v223, v15
	v_add_f32_e32 v15, v224, v15
	v_add_f32_e32 v15, v225, v15
	v_cvt_pk_bf16_f32 v222, v225, v226
	v_cvt_pk_bf16_f32 v223, v227, v228
	v_cvt_pk_bf16_f32 v224, v229, v230
	v_cvt_pk_bf16_f32 v225, v231, v232
	v_add_f32_e32 v15, v226, v15
	v_add_f32_e32 v15, v227, v15
	v_mfma_f32_32x32x16_bf16 v[64:79], v[128:131], v[222:225], v[64:79]
	v_add_f32_e32 v15, v228, v15
	v_add_f32_e32 v15, v229, v15
	s_add_i32 s13, s13, -1
	v_mfma_f32_32x32x16_bf16 v[48:63], v[140:143], v[222:225], v[48:63]
	v_add_f32_e32 v15, v230, v15
	v_add_f32_e32 v15, v231, v15
	v_mfma_f32_32x32x16_bf16 v[32:47], v[124:127], v[222:225], v[32:47]
	v_add_f32_e32 v15, v232, v15
	v_add_f32_e32 v0, v0, v15
	v_mfma_f32_32x32x16_bf16 v[16:31], v[120:123], v[222:225], v[16:31]
	s_cmp_lg_u32 s29, 0
	s_cbranch_scc1 .Lmy_pp_nbe_b
	s_waitcnt vmcnt(12) lgkmcnt(0)
	s_barrier
.Lmy_pp_nbe_b:
	s_cmp_gt_u32 s13, 1
	s_cbranch_scc1 .Lmy_pp_loop2
	v_add_u32_e32 v248, s25, v246
	v_add_u32_e32 v249, s25, v247
	ds_read_b128 v[144:147], v248 offset:8192
	ds_read_b128 v[136:139], v248 offset:10240
	ds_read_b128 v[132:135], v248 offset:12288
	ds_read_b128 v[116:119], v248 offset:14336
	ds_read_b128 v[128:131], v248 offset:9216
	ds_read_b128 v[140:143], v248 offset:11264
	ds_read_b128 v[124:127], v248 offset:13312
	ds_read_b128 v[120:123], v248 offset:15360
	v_mfma_f32_32x32x16_bf16 v[218:233], v[112:115], v[108:111], 0
	v_max3_f32 v14, v80, v81, v82
	v_max3_f32 v15, v83, v84, v85
	v_max3_f32 v209, v86, v87, v88
	s_add_i32 s27, s24, s26
	s_sub_i32 s28, 8, s29
	s_cmp_gt_u32 s13, s28
	s_cselect_b32 m0, s27, 0x20000
	s_add_i32 s28, s28, 1
	s_cmp_gt_u32 s13, s28
	s_cselect_b32 s28, -1, 0
	v_mfma_f32_32x32x16_bf16 v[218:233], v[10:13], v[104:107], v[218:233]
	v_max3_f32 v212, v89, v90, v91
	v_max3_f32 v14, v14, v92, v93
	v_max3_f32 v15, v15, v94, v95
	global_load_lds_dwordx4 v[242:243], off
	global_load_lds_dwordx4 v[242:243], off offset:1024
	v_mfma_f32_32x32x16_bf16 v[218:233], v[6:9], v[100:103], v[218:233]
	v_and_b32_e32 v244, s28, v244
	v_max3_f32 v14, v14, v15, v209
	v_max_f32_e32 v14, v14, v212
	v_lshl_add_u64 v[242:243], v[244:245], 0, v[242:243]
	v_mov_b32_e32 v15, v14
	s_add_i32 s24, s24, 0x4000
	s_and_b32 s24, s24, 0x1c000
	v_mfma_f32_32x32x16_bf16 v[218:233], v[2:5], v[96:99], v[218:233]
	v_permlane32_swap_b32_e32 v14, v15
	s_add_i32 s25, s25, 0x4000
	s_and_b32 s25, s25, 0x1c000
	v_max_f32_e32 v14, v14, v15
	v_add_f32_e32 v15, 0x41000000, v208
	v_cmp_gt_f32_e32 vcc, v14, v15
	s_cbranch_vccz .Lmy_pp_nors_t
	v_max_f32_e32 v15, v208, v14
	v_sub_f32_e32 v14, v208, v15
	v_exp_f32_e32 v14, v14
	v_mov_b32_e32 v208, v15
	s_nop 0
	v_mul_f32_e32 v0, v0, v14
	v_pk_mul_f32 v[78:79], v[78:79], v[14:15] op_sel_hi:[1,0]
	v_pk_mul_f32 v[76:77], v[76:77], v[14:15] op_sel_hi:[1,0]
	v_pk_mul_f32 v[74:75], v[74:75], v[14:15] op_sel_hi:[1,0]
	v_pk_mul_f32 v[72:73], v[72:73], v[14:15] op_sel_hi:[1,0]
	v_pk_mul_f32 v[70:71], v[70:71], v[14:15] op_sel_hi:[1,0]
	v_pk_mul_f32 v[68:69], v[68:69], v[14:15] op_sel_hi:[1,0]
	v_pk_mul_f32 v[66:67], v[66:67], v[14:15] op_sel_hi:[1,0]
	v_pk_mul_f32 v[64:65], v[64:65], v[14:15] op_sel_hi:[1,0]
	v_pk_mul_f32 v[62:63], v[62:63], v[14:15] op_sel_hi:[1,0]
	v_pk_mul_f32 v[60:61], v[60:61], v[14:15] op_sel_hi:[1,0]
	v_pk_mul_f32 v[58:59], v[58:59], v[14:15] op_sel_hi:[1,0]
	v_pk_mul_f32 v[56:57], v[56:57], v[14:15] op_sel_hi:[1,0]
	v_pk_mul_f32 v[54:55], v[54:55], v[14:15] op_sel_hi:[1,0]
	v_pk_mul_f32 v[52:53], v[52:53], v[14:15] op_sel_hi:[1,0]
	v_pk_mul_f32 v[50:51], v[50:51], v[14:15] op_sel_hi:[1,0]
	v_pk_mul_f32 v[48:49], v[48:49], v[14:15] op_sel_hi:[1,0]
	v_pk_mul_f32 v[46:47], v[46:47], v[14:15] op_sel_hi:[1,0]
	v_pk_mul_f32 v[44:45], v[44:45], v[14:15] op_sel_hi:[1,0]
	v_pk_mul_f32 v[42:43], v[42:43], v[14:15] op_sel_hi:[1,0]
	v_pk_mul_f32 v[40:41], v[40:41], v[14:15] op_sel_hi:[1,0]
	v_pk_mul_f32 v[38:39], v[38:39], v[14:15] op_sel_hi:[1,0]
	v_pk_mul_f32 v[36:37], v[36:37], v[14:15] op_sel_hi:[1,0]
	v_pk_mul_f32 v[34:35], v[34:35], v[14:15] op_sel_hi:[1,0]
	v_pk_mul_f32 v[32:33], v[32:33], v[14:15] op_sel_hi:[1,0]
	v_pk_mul_f32 v[30:31], v[30:31], v[14:15] op_sel_hi:[1,0]
	v_pk_mul_f32 v[28:29], v[28:29], v[14:15] op_sel_hi:[1,0]
	v_pk_mul_f32 v[26:27], v[26:27], v[14:15] op_sel_hi:[1,0]
	v_pk_mul_f32 v[24:25], v[24:25], v[14:15] op_sel_hi:[1,0]
	v_pk_mul_f32 v[22:23], v[22:23], v[14:15] op_sel_hi:[1,0]
	v_pk_mul_f32 v[20:21], v[20:21], v[14:15] op_sel_hi:[1,0]
	v_pk_mul_f32 v[18:19], v[18:19], v[14:15] op_sel_hi:[1,0]
	v_pk_mul_f32 v[16:17], v[16:17], v[14:15] op_sel_hi:[1,0]

.Lmy_pp_nbm_t:
	v_sub_f32_e32 v14, v80, v208
	v_exp_f32_e32 v14, v14
	v_sub_f32_e32 v80, v81, v208
	v_exp_f32_e32 v80, v80
	v_sub_f32_e32 v81, v82, v208
	v_exp_f32_e32 v81, v81
	v_sub_f32_e32 v82, v83, v208
	v_exp_f32_e32 v82, v82
	v_sub_f32_e32 v83, v84, v208
	v_sub_f32_e32 v84, v85, v208
	v_sub_f32_e32 v85, v86, v208
	v_sub_f32_e32 v86, v87, v208
	v_add_f32_e32 v15, 0, v14
	v_exp_f32_e32 v83, v83
	v_exp_f32_e32 v84, v84
	v_exp_f32_e32 v85, v85
	v_exp_f32_e32 v86, v86
	v_add_f32_e32 v15, v80, v15
	v_add_f32_e32 v15, v81, v15
	v_add_f32_e32 v15, v82, v15
	v_add_f32_e32 v15, v83, v15
	v_cvt_pk_bf16_f32 v80, v14, v80
	v_cvt_pk_bf16_f32 v81, v81, v82
	v_cvt_pk_bf16_f32 v82, v83, v84
	v_cvt_pk_bf16_f32 v83, v85, v86
	v_sub_f32_e32 v87, v88, v208
	v_sub_f32_e32 v88, v89, v208
	s_waitcnt lgkmcnt(0)
	v_mfma_f32_32x32x16_bf16 v[64:79], v[144:147], v[80:83], v[64:79]
	v_sub_f32_e32 v89, v90, v208
	v_sub_f32_e32 v90, v91, v208
	v_sub_f32_e32 v91, v92, v208
	v_exp_f32_e32 v87, v87
	v_exp_f32_e32 v88, v88
	v_mfma_f32_32x32x16_bf16 v[48:63], v[136:139], v[80:83], v[48:63]
	v_sub_f32_e32 v92, v93, v208
	v_sub_f32_e32 v93, v94, v208
	v_sub_f32_e32 v94, v95, v208
	v_exp_f32_e32 v89, v89
	v_exp_f32_e32 v90, v90
	v_mfma_f32_32x32x16_bf16 v[32:47], v[132:135], v[80:83], v[32:47]
	v_exp_f32_e32 v91, v91
	v_exp_f32_e32 v92, v92
	v_exp_f32_e32 v93, v93
	v_exp_f32_e32 v94, v94
	v_mfma_f32_32x32x16_bf16 v[16:31], v[116:119], v[80:83], v[16:31]
	v_add_f32_e32 v15, v84, v15
	v_add_f32_e32 v15, v85, v15
	v_add_f32_e32 v15, v86, v15
	v_add_f32_e32 v15, v87, v15
	v_cvt_pk_bf16_f32 v84, v87, v88
	v_cvt_pk_bf16_f32 v85, v89, v90
	v_cvt_pk_bf16_f32 v86, v91, v92
	v_cvt_pk_bf16_f32 v87, v93, v94
	v_add_f32_e32 v15, v88, v15
	v_add_f32_e32 v15, v89, v15
	v_mfma_f32_32x32x16_bf16 v[64:79], v[128:131], v[84:87], v[64:79]
	v_add_f32_e32 v15, v90, v15
	v_add_f32_e32 v15, v91, v15
	s_add_i32 s13, s13, -1
	v_mfma_f32_32x32x16_bf16 v[48:63], v[140:143], v[84:87], v[48:63]
	v_add_f32_e32 v15, v92, v15
	v_add_f32_e32 v15, v93, v15
	v_mfma_f32_32x32x16_bf16 v[32:47], v[124:127], v[84:87], v[32:47]
	v_add_f32_e32 v15, v94, v15
	v_add_f32_e32 v0, v0, v15
	v_mfma_f32_32x32x16_bf16 v[16:31], v[120:123], v[84:87], v[16:31]
	s_cmp_lg_u32 s29, 0
	s_cbranch_scc1 .Lmy_pp_nbe_t
	s_waitcnt vmcnt(12) lgkmcnt(0)
	s_barrier
